# adds: top-k histogram pass without the bin clamp (scale 255.996 keeps every bin below 256)
# baseline (speedup 1.0000x reference)
; #define DSA_LWAIT() asm volatile("s_waitcnt lgkmcnt(0)" ::: "memory")
; #define SMF_FOR(...) { _Pragma("unroll 4") for (int j = 0; j < R - 1; ++j) { const int key = 64 * j + lane; const float v = row[key]; (void)key; __VA_ARGS__ } \
;                        { const int key = 64 * (R - 1) + lane; if (key < nv) { const float v = row[key]; __VA_ARGS__ } } }
; __device__ __forceinline__ bool select_mask_fast(const LAS float* row, int nv, int ksel, LAS unsigned* scr, int lane, u64& word_o) {
;     ...
;     const float lo = wave_min(m3), hi = wave_max(m0);
;     if (ksel > 256 || !(lo > -INFINITY) || !(hi - lo > 1e-30f)) return false;
;     const float scale = 256.0f / (hi - lo), nls = -lo * scale;
; #pragma unroll
;     for (int k = 0; k < 4; ++k) hist[4 * lane + k] = 0u;
;     if (lane == 0) cnt[0] = 0u;
;     DSA_LWAIT();
;     SMF_FOR({ if (v >= lo) { int bin = (int)fmaf(v, scale, nls); bin = bin > 255 ? 255 : bin; bin = bin < 0 ? 0 : bin; __hip_atomic_fetch_add(&hist[bin], 1u, __ATOMIC_RELAXED, __HIP_MEMORY_SCOPE_WORKGROUP); } })
.Lnsel_p1done:
	s_nop 1
	v_max_f32_dpp v114, v114, v114 quad_perm:[1,0,3,2] row_mask:0xf bank_mask:0xf
	v_min_f32_dpp v117, v117, v117 quad_perm:[1,0,3,2] row_mask:0xf bank_mask:0xf
	s_nop 1
	v_max_f32_dpp v114, v114, v114 quad_perm:[2,3,0,1] row_mask:0xf bank_mask:0xf
	v_min_f32_dpp v117, v117, v117 quad_perm:[2,3,0,1] row_mask:0xf bank_mask:0xf
	s_nop 1
	v_max_f32_dpp v114, v114, v114 row_half_mirror row_mask:0xf bank_mask:0xf
	v_min_f32_dpp v117, v117, v117 row_half_mirror row_mask:0xf bank_mask:0xf
	s_nop 1
	v_max_f32_dpp v114, v114, v114 row_mirror row_mask:0xf bank_mask:0xf
	v_min_f32_dpp v117, v117, v117 row_mirror row_mask:0xf bank_mask:0xf
	s_nop 1
	v_max_f32_dpp v114, v114, v114 row_bcast:15 row_mask:0xa bank_mask:0xf
	v_min_f32_dpp v117, v117, v117 row_bcast:15 row_mask:0xa bank_mask:0xf
	s_nop 1
	v_max_f32_dpp v114, v114, v114 row_bcast:31 row_mask:0xc bank_mask:0xf
	v_min_f32_dpp v117, v117, v117 row_bcast:31 row_mask:0xc bank_mask:0xf
	s_nop 1
	v_readlane_b32 s73, v114, 63
	v_readlane_b32 s72, v117, 63
	s_nop 1
	v_mov_b32_e32 v130, s72
	v_sub_f32_e32 v131, s73, v130
	v_cmp_lg_f32_e32 vcc, s90, v130
	s_mov_b64 s[78:79], vcc
	v_cmp_lt_f32_e32 vcc, s91, v131
	s_and_b64 vcc, vcc, s[78:79]
	v_rcp_f32_e32 v128, v131
	s_cbranch_vccz .Lnsel_bail
	v_mul_f32_e32 v128, 0x437fff00, v128
	v_mul_f32_e64 v129, v128, -v130
	ds_write_b128 v147, v[216:219]
	s_waitcnt lgkmcnt(0)
	v_cmp_le_f32_e64 s[78:79], s72, v2
	v_cmp_le_f32_e64 s[80:81], s72, v3
	v_cmp_le_f32_e64 s[82:83], s72, v4
	v_cmp_le_f32_e64 s[84:85], s72, v5
	v_fma_f32 v2, v2, v128, v129
	v_fma_f32 v3, v3, v128, v129
	v_fma_f32 v4, v4, v128, v129
	v_fma_f32 v5, v5, v128, v129
	v_cvt_i32_f32_e32 v122, v2
	v_cvt_i32_f32_e32 v123, v3
	v_cvt_i32_f32_e32 v124, v4
	v_cvt_i32_f32_e32 v125, v5
	v_lshl_add_u32 v122, v122, 2, s10
	v_lshl_add_u32 v123, v123, 2, s10
	v_lshl_add_u32 v124, v124, 2, s10
	v_lshl_add_u32 v125, v125, 2, s10
	s_mov_b64 exec, s[78:79]
	ds_add_u32 v122, v239
	s_mov_b64 exec, s[80:81]
	ds_add_u32 v123, v239
	s_mov_b64 exec, s[82:83]
	ds_add_u32 v124, v239
	s_mov_b64 exec, s[84:85]
	ds_add_u32 v125, v239
	s_mov_b64 exec, -1
	s_cmp_le_u32 s70, 4
	s_cbranch_scc1 .Lnsel_histdone
	v_cmp_le_f32_e64 s[78:79], s72, v6
	v_cmp_le_f32_e64 s[80:81], s72, v7
	v_cmp_le_f32_e64 s[82:83], s72, v8
	v_cmp_le_f32_e64 s[84:85], s72, v9
	v_fma_f32 v6, v6, v128, v129
	v_fma_f32 v7, v7, v128, v129
	v_fma_f32 v8, v8, v128, v129
	v_fma_f32 v9, v9, v128, v129
	v_cvt_i32_f32_e32 v122, v6
	v_cvt_i32_f32_e32 v123, v7
	v_cvt_i32_f32_e32 v124, v8
	v_cvt_i32_f32_e32 v125, v9
	v_lshl_add_u32 v122, v122, 2, s10
	v_lshl_add_u32 v123, v123, 2, s10
	v_lshl_add_u32 v124, v124, 2, s10
	v_lshl_add_u32 v125, v125, 2, s10
	s_mov_b64 exec, s[78:79]
	ds_add_u32 v122, v239
	s_mov_b64 exec, s[80:81]
	ds_add_u32 v123, v239
	s_mov_b64 exec, s[82:83]
	ds_add_u32 v124, v239
	s_mov_b64 exec, s[84:85]
	ds_add_u32 v125, v239
	s_mov_b64 exec, -1
	s_cmp_le_u32 s70, 8
	s_cbranch_scc1 .Lnsel_histdone
	v_cmp_le_f32_e64 s[78:79], s72, v10
	v_cmp_le_f32_e64 s[80:81], s72, v11
	v_cmp_le_f32_e64 s[82:83], s72, v12
	v_cmp_le_f32_e64 s[84:85], s72, v13
	v_fma_f32 v10, v10, v128, v129
	v_fma_f32 v11, v11, v128, v129
	v_fma_f32 v12, v12, v128, v129
	v_fma_f32 v13, v13, v128, v129
	v_cvt_i32_f32_e32 v122, v10
	v_cvt_i32_f32_e32 v123, v11
	v_cvt_i32_f32_e32 v124, v12
	v_cvt_i32_f32_e32 v125, v13
	v_lshl_add_u32 v122, v122, 2, s10
	v_lshl_add_u32 v123, v123, 2, s10
	v_lshl_add_u32 v124, v124, 2, s10
	v_lshl_add_u32 v125, v125, 2, s10
	s_mov_b64 exec, s[78:79]
	ds_add_u32 v122, v239
	s_mov_b64 exec, s[80:81]
	ds_add_u32 v123, v239
	s_mov_b64 exec, s[82:83]
	ds_add_u32 v124, v239
	s_mov_b64 exec, s[84:85]
	ds_add_u32 v125, v239
	s_mov_b64 exec, -1
	s_cmp_le_u32 s70, 12
	s_cbranch_scc1 .Lnsel_histdone
	v_cmp_le_f32_e64 s[78:79], s72, v14
	v_cmp_le_f32_e64 s[80:81], s72, v15
	v_cmp_le_f32_e64 s[82:83], s72, v16
	v_cmp_le_f32_e64 s[84:85], s72, v17
	v_fma_f32 v14, v14, v128, v129
	v_fma_f32 v15, v15, v128, v129
	v_fma_f32 v16, v16, v128, v129
	v_fma_f32 v17, v17, v128, v129
	v_cvt_i32_f32_e32 v122, v14
	v_cvt_i32_f32_e32 v123, v15
	v_cvt_i32_f32_e32 v124, v16
	v_cvt_i32_f32_e32 v125, v17
	v_lshl_add_u32 v122, v122, 2, s10
	v_lshl_add_u32 v123, v123, 2, s10
	v_lshl_add_u32 v124, v124, 2, s10
	v_lshl_add_u32 v125, v125, 2, s10
	s_mov_b64 exec, s[78:79]
	ds_add_u32 v122, v239
	s_mov_b64 exec, s[80:81]
	ds_add_u32 v123, v239
	s_mov_b64 exec, s[82:83]
	ds_add_u32 v124, v239
	s_mov_b64 exec, s[84:85]
	ds_add_u32 v125, v239
	s_mov_b64 exec, -1
	s_cmp_le_u32 s70, 16
	s_cbranch_scc1 .Lnsel_histdone
	v_cmp_le_f32_e64 s[78:79], s72, v18
	v_cmp_le_f32_e64 s[80:81], s72, v19
	v_cmp_le_f32_e64 s[82:83], s72, v20
	v_cmp_le_f32_e64 s[84:85], s72, v21
	v_fma_f32 v18, v18, v128, v129
	v_fma_f32 v19, v19, v128, v129
	v_fma_f32 v20, v20, v128, v129
	v_fma_f32 v21, v21, v128, v129
	v_cvt_i32_f32_e32 v122, v18
	v_cvt_i32_f32_e32 v123, v19
	v_cvt_i32_f32_e32 v124, v20
	v_cvt_i32_f32_e32 v125, v21
	v_lshl_add_u32 v122, v122, 2, s10
	v_lshl_add_u32 v123, v123, 2, s10
	v_lshl_add_u32 v124, v124, 2, s10
	v_lshl_add_u32 v125, v125, 2, s10
	s_mov_b64 exec, s[78:79]
	ds_add_u32 v122, v239
	s_mov_b64 exec, s[80:81]
	ds_add_u32 v123, v239
	s_mov_b64 exec, s[82:83]
	ds_add_u32 v124, v239
	s_mov_b64 exec, s[84:85]
	ds_add_u32 v125, v239
	s_mov_b64 exec, -1
	s_cmp_le_u32 s70, 20
	s_cbranch_scc1 .Lnsel_histdone
; #define SMF_FOR(...) { _Pragma("unroll 4") for (int j = 0; j < R - 1; ++j) { const int key = 64 * j + lane; const float v = row[key]; (void)key; __VA_ARGS__ } \
;                        { const int key = 64 * (R - 1) + lane; if (key < nv) { const float v = row[key]; __VA_ARGS__ } } }
; __device__ __forceinline__ bool select_mask_fast(const LAS float* row, int nv, int ksel, LAS unsigned* scr, int lane, u64& word_o) {
;     ...
;     SMF_FOR({ if (v >= lo) { int bin = (int)fmaf(v, scale, nls); bin = bin > 255 ? 255 : bin; bin = bin < 0 ? 0 : bin; __hip_atomic_fetch_add(&hist[bin], 1u, __ATOMIC_RELAXED, __HIP_MEMORY_SCOPE_WORKGROUP); } })
	v_cmp_le_f32_e64 s[78:79], s72, v22
	v_cmp_le_f32_e64 s[80:81], s72, v23
	v_cmp_le_f32_e64 s[82:83], s72, v24
	v_cmp_le_f32_e64 s[84:85], s72, v25
	v_fma_f32 v22, v22, v128, v129
	v_fma_f32 v23, v23, v128, v129
	v_fma_f32 v24, v24, v128, v129
	v_fma_f32 v25, v25, v128, v129
	v_cvt_i32_f32_e32 v122, v22
	v_cvt_i32_f32_e32 v123, v23
	v_cvt_i32_f32_e32 v124, v24
	v_cvt_i32_f32_e32 v125, v25
	v_lshl_add_u32 v122, v122, 2, s10
	v_lshl_add_u32 v123, v123, 2, s10
	v_lshl_add_u32 v124, v124, 2, s10
	v_lshl_add_u32 v125, v125, 2, s10
	s_mov_b64 exec, s[78:79]
	ds_add_u32 v122, v239
	s_mov_b64 exec, s[80:81]
	ds_add_u32 v123, v239
	s_mov_b64 exec, s[82:83]
	ds_add_u32 v124, v239
	s_mov_b64 exec, s[84:85]
	ds_add_u32 v125, v239
	s_mov_b64 exec, -1
	s_cmp_le_u32 s70, 24
	s_cbranch_scc1 .Lnsel_histdone
	v_cmp_le_f32_e64 s[78:79], s72, v26
	v_cmp_le_f32_e64 s[80:81], s72, v27
	v_cmp_le_f32_e64 s[82:83], s72, v28
	v_cmp_le_f32_e64 s[84:85], s72, v29
	v_fma_f32 v26, v26, v128, v129
	v_fma_f32 v27, v27, v128, v129
	v_fma_f32 v28, v28, v128, v129
	v_fma_f32 v29, v29, v128, v129
	v_cvt_i32_f32_e32 v122, v26
	v_cvt_i32_f32_e32 v123, v27
	v_cvt_i32_f32_e32 v124, v28
	v_cvt_i32_f32_e32 v125, v29
	v_lshl_add_u32 v122, v122, 2, s10
	v_lshl_add_u32 v123, v123, 2, s10
	v_lshl_add_u32 v124, v124, 2, s10
	v_lshl_add_u32 v125, v125, 2, s10
	s_mov_b64 exec, s[78:79]
	ds_add_u32 v122, v239
	s_mov_b64 exec, s[80:81]
	ds_add_u32 v123, v239
	s_mov_b64 exec, s[82:83]
	ds_add_u32 v124, v239
	s_mov_b64 exec, s[84:85]
	ds_add_u32 v125, v239
	s_mov_b64 exec, -1
	s_cmp_le_u32 s70, 28
	s_cbranch_scc1 .Lnsel_histdone
	v_cmp_le_f32_e64 s[78:79], s72, v30
	v_cmp_le_f32_e64 s[80:81], s72, v31
	v_cmp_le_f32_e64 s[82:83], s72, v32
	v_cmp_le_f32_e64 s[84:85], s72, v33
	v_fma_f32 v30, v30, v128, v129
	v_fma_f32 v31, v31, v128, v129
	v_fma_f32 v32, v32, v128, v129
	v_fma_f32 v33, v33, v128, v129
	v_cvt_i32_f32_e32 v122, v30
	v_cvt_i32_f32_e32 v123, v31
	v_cvt_i32_f32_e32 v124, v32
	v_cvt_i32_f32_e32 v125, v33
	v_lshl_add_u32 v122, v122, 2, s10
	v_lshl_add_u32 v123, v123, 2, s10
	v_lshl_add_u32 v124, v124, 2, s10
	v_lshl_add_u32 v125, v125, 2, s10
	s_mov_b64 exec, s[78:79]
	ds_add_u32 v122, v239
	s_mov_b64 exec, s[80:81]
	ds_add_u32 v123, v239
	s_mov_b64 exec, s[82:83]
	ds_add_u32 v124, v239
	s_mov_b64 exec, s[84:85]
	ds_add_u32 v125, v239
	s_mov_b64 exec, -1
	s_cmp_le_u32 s70, 32
	s_cbranch_scc1 .Lnsel_histdone
	v_cmp_le_f32_e64 s[78:79], s72, v34
	v_cmp_le_f32_e64 s[80:81], s72, v35
	v_cmp_le_f32_e64 s[82:83], s72, v36
	v_cmp_le_f32_e64 s[84:85], s72, v37
	v_fma_f32 v34, v34, v128, v129
	v_fma_f32 v35, v35, v128, v129
	v_fma_f32 v36, v36, v128, v129
	v_fma_f32 v37, v37, v128, v129
	v_cvt_i32_f32_e32 v122, v34
	v_cvt_i32_f32_e32 v123, v35
	v_cvt_i32_f32_e32 v124, v36
	v_cvt_i32_f32_e32 v125, v37
	v_lshl_add_u32 v122, v122, 2, s10
	v_lshl_add_u32 v123, v123, 2, s10
	v_lshl_add_u32 v124, v124, 2, s10
	v_lshl_add_u32 v125, v125, 2, s10
	s_mov_b64 exec, s[78:79]
	ds_add_u32 v122, v239
	s_mov_b64 exec, s[80:81]
	ds_add_u32 v123, v239
	s_mov_b64 exec, s[82:83]
	ds_add_u32 v124, v239
	s_mov_b64 exec, s[84:85]
	ds_add_u32 v125, v239
	s_mov_b64 exec, -1
	s_cmp_le_u32 s70, 36
	s_cbranch_scc1 .Lnsel_histdone
	v_cmp_le_f32_e64 s[78:79], s72, v38
	v_cmp_le_f32_e64 s[80:81], s72, v39
	v_cmp_le_f32_e64 s[82:83], s72, v40
	v_cmp_le_f32_e64 s[84:85], s72, v41
	v_fma_f32 v38, v38, v128, v129
	v_fma_f32 v39, v39, v128, v129
	v_fma_f32 v40, v40, v128, v129
	v_fma_f32 v41, v41, v128, v129
	v_cvt_i32_f32_e32 v122, v38
	v_cvt_i32_f32_e32 v123, v39
	v_cvt_i32_f32_e32 v124, v40
	v_cvt_i32_f32_e32 v125, v41
	v_lshl_add_u32 v122, v122, 2, s10
	v_lshl_add_u32 v123, v123, 2, s10
	v_lshl_add_u32 v124, v124, 2, s10
	v_lshl_add_u32 v125, v125, 2, s10
	s_mov_b64 exec, s[78:79]
	ds_add_u32 v122, v239
	s_mov_b64 exec, s[80:81]
	ds_add_u32 v123, v239
	s_mov_b64 exec, s[82:83]
	ds_add_u32 v124, v239
	s_mov_b64 exec, s[84:85]
	ds_add_u32 v125, v239
	s_mov_b64 exec, -1
	s_cmp_le_u32 s70, 40
	s_cbranch_scc1 .Lnsel_histdone
; #define SMF_FOR(...) { _Pragma("unroll 4") for (int j = 0; j < R - 1; ++j) { const int key = 64 * j + lane; const float v = row[key]; (void)key; __VA_ARGS__ } \
;                        { const int key = 64 * (R - 1) + lane; if (key < nv) { const float v = row[key]; __VA_ARGS__ } } }
; __device__ __forceinline__ bool select_mask_fast(const LAS float* row, int nv, int ksel, LAS unsigned* scr, int lane, u64& word_o) {
;     ...
;     SMF_FOR({ if (v >= lo) { int bin = (int)fmaf(v, scale, nls); bin = bin > 255 ? 255 : bin; bin = bin < 0 ? 0 : bin; __hip_atomic_fetch_add(&hist[bin], 1u, __ATOMIC_RELAXED, __HIP_MEMORY_SCOPE_WORKGROUP); } })
	v_cmp_le_f32_e64 s[78:79], s72, v42
	v_cmp_le_f32_e64 s[80:81], s72, v43
	v_cmp_le_f32_e64 s[82:83], s72, v44
	v_cmp_le_f32_e64 s[84:85], s72, v45
	v_fma_f32 v42, v42, v128, v129
	v_fma_f32 v43, v43, v128, v129
	v_fma_f32 v44, v44, v128, v129
	v_fma_f32 v45, v45, v128, v129
	v_cvt_i32_f32_e32 v122, v42
	v_cvt_i32_f32_e32 v123, v43
	v_cvt_i32_f32_e32 v124, v44
	v_cvt_i32_f32_e32 v125, v45
	v_lshl_add_u32 v122, v122, 2, s10
	v_lshl_add_u32 v123, v123, 2, s10
	v_lshl_add_u32 v124, v124, 2, s10
	v_lshl_add_u32 v125, v125, 2, s10
	s_mov_b64 exec, s[78:79]
	ds_add_u32 v122, v239
	s_mov_b64 exec, s[80:81]
	ds_add_u32 v123, v239
	s_mov_b64 exec, s[82:83]
	ds_add_u32 v124, v239
	s_mov_b64 exec, s[84:85]
	ds_add_u32 v125, v239
	s_mov_b64 exec, -1
	s_cmp_le_u32 s70, 44
	s_cbranch_scc1 .Lnsel_histdone
	v_cmp_le_f32_e64 s[78:79], s72, v46
	v_cmp_le_f32_e64 s[80:81], s72, v47
	v_cmp_le_f32_e64 s[82:83], s72, v48
	v_cmp_le_f32_e64 s[84:85], s72, v49
	v_fma_f32 v46, v46, v128, v129
	v_fma_f32 v47, v47, v128, v129
	v_fma_f32 v48, v48, v128, v129
	v_fma_f32 v49, v49, v128, v129
	v_cvt_i32_f32_e32 v122, v46
	v_cvt_i32_f32_e32 v123, v47
	v_cvt_i32_f32_e32 v124, v48
	v_cvt_i32_f32_e32 v125, v49
	v_lshl_add_u32 v122, v122, 2, s10
	v_lshl_add_u32 v123, v123, 2, s10
	v_lshl_add_u32 v124, v124, 2, s10
	v_lshl_add_u32 v125, v125, 2, s10
	s_mov_b64 exec, s[78:79]
	ds_add_u32 v122, v239
	s_mov_b64 exec, s[80:81]
	ds_add_u32 v123, v239
	s_mov_b64 exec, s[82:83]
	ds_add_u32 v124, v239
	s_mov_b64 exec, s[84:85]
	ds_add_u32 v125, v239
	s_mov_b64 exec, -1
	s_cmp_le_u32 s70, 48
	s_cbranch_scc1 .Lnsel_histdone
	v_cmp_le_f32_e64 s[78:79], s72, v50
	v_cmp_le_f32_e64 s[80:81], s72, v51
	v_cmp_le_f32_e64 s[82:83], s72, v52
	v_cmp_le_f32_e64 s[84:85], s72, v53
	v_fma_f32 v50, v50, v128, v129
	v_fma_f32 v51, v51, v128, v129
	v_fma_f32 v52, v52, v128, v129
	v_fma_f32 v53, v53, v128, v129
	v_cvt_i32_f32_e32 v122, v50
	v_cvt_i32_f32_e32 v123, v51
	v_cvt_i32_f32_e32 v124, v52
	v_cvt_i32_f32_e32 v125, v53
	v_lshl_add_u32 v122, v122, 2, s10
	v_lshl_add_u32 v123, v123, 2, s10
	v_lshl_add_u32 v124, v124, 2, s10
	v_lshl_add_u32 v125, v125, 2, s10
	s_mov_b64 exec, s[78:79]
	ds_add_u32 v122, v239
	s_mov_b64 exec, s[80:81]
	ds_add_u32 v123, v239
	s_mov_b64 exec, s[82:83]
	ds_add_u32 v124, v239
	s_mov_b64 exec, s[84:85]
	ds_add_u32 v125, v239
	s_mov_b64 exec, -1
	s_cmp_le_u32 s70, 52
	s_cbranch_scc1 .Lnsel_histdone
	v_cmp_le_f32_e64 s[78:79], s72, v54
	v_cmp_le_f32_e64 s[80:81], s72, v55
	v_cmp_le_f32_e64 s[82:83], s72, v56
	v_cmp_le_f32_e64 s[84:85], s72, v57
	v_fma_f32 v54, v54, v128, v129
	v_fma_f32 v55, v55, v128, v129
	v_fma_f32 v56, v56, v128, v129
	v_fma_f32 v57, v57, v128, v129
	v_cvt_i32_f32_e32 v122, v54
	v_cvt_i32_f32_e32 v123, v55
	v_cvt_i32_f32_e32 v124, v56
	v_cvt_i32_f32_e32 v125, v57
	v_lshl_add_u32 v122, v122, 2, s10
	v_lshl_add_u32 v123, v123, 2, s10
	v_lshl_add_u32 v124, v124, 2, s10
	v_lshl_add_u32 v125, v125, 2, s10
	s_mov_b64 exec, s[78:79]
	ds_add_u32 v122, v239
	s_mov_b64 exec, s[80:81]
	ds_add_u32 v123, v239
	s_mov_b64 exec, s[82:83]
	ds_add_u32 v124, v239
	s_mov_b64 exec, s[84:85]
	ds_add_u32 v125, v239
	s_mov_b64 exec, -1
	s_cmp_le_u32 s70, 56
	s_cbranch_scc1 .Lnsel_histdone
	v_cmp_le_f32_e64 s[78:79], s72, v58
	v_cmp_le_f32_e64 s[80:81], s72, v59
	v_cmp_le_f32_e64 s[82:83], s72, v60
	v_cmp_le_f32_e64 s[84:85], s72, v61
	v_fma_f32 v58, v58, v128, v129
	v_fma_f32 v59, v59, v128, v129
	v_fma_f32 v60, v60, v128, v129
	v_fma_f32 v61, v61, v128, v129
	v_cvt_i32_f32_e32 v122, v58
	v_cvt_i32_f32_e32 v123, v59
	v_cvt_i32_f32_e32 v124, v60
	v_cvt_i32_f32_e32 v125, v61
	v_lshl_add_u32 v122, v122, 2, s10
	v_lshl_add_u32 v123, v123, 2, s10
	v_lshl_add_u32 v124, v124, 2, s10
	v_lshl_add_u32 v125, v125, 2, s10
	s_mov_b64 exec, s[78:79]
	ds_add_u32 v122, v239
	s_mov_b64 exec, s[80:81]
	ds_add_u32 v123, v239
	s_mov_b64 exec, s[82:83]
	ds_add_u32 v124, v239
	s_mov_b64 exec, s[84:85]
	ds_add_u32 v125, v239
	s_mov_b64 exec, -1
	s_cmp_le_u32 s70, 60
	s_cbranch_scc1 .Lnsel_histdone
	v_cmp_le_f32_e64 s[78:79], s72, v62
	v_cmp_le_f32_e64 s[80:81], s72, v63
	v_cmp_le_f32_e64 s[82:83], s72, v64
	v_cmp_le_f32_e64 s[84:85], s72, v65
	v_fma_f32 v62, v62, v128, v129
	v_fma_f32 v63, v63, v128, v129
	v_fma_f32 v64, v64, v128, v129
	v_fma_f32 v65, v65, v128, v129
	v_cvt_i32_f32_e32 v122, v62
	v_cvt_i32_f32_e32 v123, v63
	v_cvt_i32_f32_e32 v124, v64
	v_cvt_i32_f32_e32 v125, v65
	v_lshl_add_u32 v122, v122, 2, s10
	v_lshl_add_u32 v123, v123, 2, s10
	v_lshl_add_u32 v124, v124, 2, s10
	v_lshl_add_u32 v125, v125, 2, s10
	s_mov_b64 exec, s[78:79]
	ds_add_u32 v122, v239
	s_mov_b64 exec, s[80:81]
	ds_add_u32 v123, v239
	s_mov_b64 exec, s[82:83]
	ds_add_u32 v124, v239
	s_mov_b64 exec, s[84:85]
	ds_add_u32 v125, v239
	s_mov_b64 exec, -1
